# MIX1: half of the workgroups (blockIdx bit 3) run the sub-phases in rotated order sret,copies,kv,attn,sattn so HBM streaming overlaps the latency-bound units
# baseline (speedup 1.0000x reference)
.LBB0_971:
	s_bitcmp1_b32 s34, 3
	s_cbranch_scc1 .Lmix_toD

.Lmix_toD:
	v_lshrrev_b32_e32 v96, 7, v128
	s_branch .Lmix_D
.LBB0_1097:
	s_or_b64 exec, exec, s[18:19]
	s_bitcmp1_b32 s34, 3
	s_cbranch_scc1 .Lmix_A
